# retS state MFMA chain: fragment reads issued up to 7 ahead into a register ring with counted lgkmcnt (was one LDS round trip per MFMA)
# speedup vs baseline: 1.0033x; 1.0033x over previous
.LBB0_64:
	s_mov_b64 s[0:1], s[12:13]
	s_mov_b64 s[0:1], s[14:15]
	s_mov_b64 s[0:1], s[16:17]
	s_mov_b64 s[0:1], s[18:19]
	s_mov_b64 s[0:1], s[20:21]
	s_mov_b64 s[0:1], s[22:23]
	s_mov_b64 s[0:1], s[24:25]
	s_mov_b64 s[0:1], s[26:27]
	v_readlane_b32 s36, v243, 22
	v_readlane_b32 s37, v243, 23
	s_mov_b64 s[0:1], s[36:37]
	v_readlane_b32 s38, v243, 24
	v_readlane_b32 s39, v243, 25
	s_mov_b64 s[0:1], s[38:39]
	v_readlane_b32 s40, v243, 26
	v_readlane_b32 s41, v243, 27
	s_mov_b64 s[0:1], s[40:41]
	v_readlane_b32 s42, v243, 28
	v_readlane_b32 s43, v243, 29
	s_mov_b64 s[0:1], s[42:43]
	v_readlane_b32 s44, v243, 30
	v_readlane_b32 s45, v243, 31
	s_mov_b64 s[0:1], s[44:45]
	v_readlane_b32 s46, v243, 32
	v_readlane_b32 s47, v243, 33
	s_mov_b64 s[0:1], s[46:47]
	v_readlane_b32 s48, v243, 34
	v_readlane_b32 s49, v243, 35
	s_mov_b64 s[0:1], s[48:49]
	v_readlane_b32 s50, v243, 36
	v_readlane_b32 s51, v243, 37
	s_mov_b64 s[0:1], s[50:51]
	s_mov_b64 s[0:1], s[52:53]
	s_mov_b64 s[0:1], s[54:55]
	s_mov_b64 s[0:1], s[56:57]
	s_mov_b64 s[0:1], s[58:59]
	s_mov_b64 s[0:1], s[60:61]
	s_mov_b64 s[0:1], s[62:63]
	s_mov_b64 s[8:9], s[64:65]
	s_mov_b64 s[0:1], s[66:67]
	v_readlane_b32 s36, v243, 5
	v_readlane_b32 s37, v243, 6
	s_mov_b64 s[0:1], s[36:37]
	v_readlane_b32 s38, v243, 7
	v_readlane_b32 s39, v243, 8
	s_mov_b64 s[0:1], s[38:39]
	v_readlane_b32 s40, v243, 9
	v_readlane_b32 s41, v243, 10
	s_mov_b64 s[0:1], s[40:41]
	v_readlane_b32 s68, v243, 1
	v_readlane_b32 s42, v243, 11
	v_readlane_b32 s43, v243, 12
	v_readlane_b32 s69, v243, 2
	v_readlane_b32 s70, v243, 3
	v_readlane_b32 s71, v243, 4
	s_mov_b64 s[0:1], s[42:43]
	s_mov_b64 s[30:31], s[68:69]
	s_mov_b64 s[4:5], s[70:71]
	s_add_i32 s10, s2, s3
	s_ashr_i32 s4, s10, 7
	s_and_b32 s28, s10, 31
	s_ashr_i32 s5, s4, 31
	s_lshl_b64 s[68:69], s[4:5], 12
	s_lshl_b32 s5, s28, 7
	s_or_b32 s5, s68, s5
	s_bfe_u32 s29, s10, 0x20005
	s_mul_i32 s10, s69, 0x1e00
	s_mul_hi_u32 s68, s5, 0x1e00
	s_add_i32 s68, s68, s10
	s_mulk_i32 s5, 0x1e00
	s_add_u32 s8, s8, s5
	s_addc_u32 s9, s9, s68
	s_add_u32 s68, s98, s29
	s_addc_u32 s69, s99, 0
	v_mov_b32_e32 v51, v200
	s_lshl_b64 s[68:69], s[68:69], 2
	s_movk_i32 s38, 0x1e00
	s_add_u32 s30, s30, s68
	v_ashrrev_i32_e32 v5, 3, v51
	v_mov_b64_e32 v[2:3], s[8:9]
	s_addc_u32 s31, s31, s69
	v_lshlrev_b32_e32 v0, 4, v51
	v_mad_i64_i32 v[8:9], s[8:9], v5, s38, v[2:3]
	s_lshl_b32 s10, s29, 7
	v_and_b32_e32 v0, 0x70, v0
	v_lshl_add_u64 v[8:9], v[8:9], 0, s[10:11]
	global_load_dword v7, v1, s[30:31] offset:8
	global_load_dword v6, v1, s[30:31] offset:24
	v_lshl_add_u64 v[8:9], v[8:9], 0, v[0:1]
	s_movk_i32 s5, 0x1000
	v_add_co_u32_e32 v8, vcc, s5, v8
	v_sub_u32_e32 v12, 0x7f, v5
	s_nop 0
	v_addc_co_u32_e32 v9, vcc, 0, v9, vcc
	v_add_co_u32_e32 v130, vcc, 0x3c000, v8
	s_nop 1
	v_addc_co_u32_e32 v131, vcc, 0, v9, vcc
	v_add_co_u32_e32 v132, vcc, 0x78000, v8
	s_nop 1
	v_addc_co_u32_e32 v133, vcc, 0, v9, vcc
	v_add_co_u32_e32 v134, vcc, 0xb4000, v8
	s_nop 1
	v_addc_co_u32_e32 v135, vcc, 0, v9, vcc
	global_load_dwordx4 v[8:11], v[8:9], off offset:1536
	global_load_dwordx4 v[136:139], v[130:131], off offset:1536
	global_load_dwordx4 v[140:143], v[132:133], off offset:1536
	global_load_dwordx4 v[144:147], v[134:135], off offset:1536
	v_cvt_f32_i32_e32 v12, v12
	v_cvt_f32_i32_e32 v13, v5
	s_movk_i32 s30, 0x90
	s_mov_b32 s31, 0x2aaaaaab
	s_movk_i32 s36, 0xd0
	v_lshlrev_b32_e32 v4, 3, v51
	v_and_b32_e32 v4, 24, v4
	s_waitcnt vmcnt(5)
	v_mul_f32_e32 v12, v7, v12
	v_exp_f32_e32 v12, v12
	s_waitcnt vmcnt(4)
	v_mul_f32_e32 v13, v6, v13
	v_exp_f32_e32 v14, v13
	s_waitcnt vmcnt(3)
	v_lshlrev_b32_e32 v16, 16, v8
	v_and_b32_e32 v17, 0xffff0000, v8
	v_pk_mul_f32 v[18:19], v[12:13], v[16:17] op_sel_hi:[0,1]
	v_cvt_pk_bf16_f32 v8, v18, v19
	v_lshlrev_b32_e32 v18, 16, v9
	v_and_b32_e32 v19, 0xffff0000, v9
	v_pk_mul_f32 v[20:21], v[12:13], v[18:19] op_sel_hi:[0,1]
	v_cvt_pk_bf16_f32 v9, v20, v21
	v_lshlrev_b32_e32 v20, 16, v10
	v_and_b32_e32 v21, 0xffff0000, v10
	v_pk_mul_f32 v[22:23], v[12:13], v[20:21] op_sel_hi:[0,1]
	v_cvt_pk_bf16_f32 v10, v22, v23
	v_lshlrev_b32_e32 v22, 16, v11
	v_and_b32_e32 v23, 0xffff0000, v11
	v_pk_mul_f32 v[12:13], v[12:13], v[22:23] op_sel_hi:[0,1]
	v_cvt_pk_bf16_f32 v11, v12, v13
	v_mad_u64_u32 v[12:13], s[8:9], v5, s30, v[0:1]
	ds_write_b128 v12, v[8:11]
	v_pk_mul_f32 v[8:9], v[14:15], v[16:17] op_sel_hi:[0,1]
	v_pk_mul_f32 v[10:11], v[14:15], v[18:19] op_sel_hi:[0,1]
	v_cvt_pk_bf16_f32 v8, v8, v9
	v_cvt_pk_bf16_f32 v9, v10, v11
	v_pk_mul_f32 v[10:11], v[14:15], v[20:21] op_sel_hi:[0,1]
	v_pk_mul_f32 v[14:15], v[14:15], v[22:23] op_sel_hi:[0,1]
	v_add_u32_e32 v5, 0x100, v51
	v_cvt_pk_bf16_f32 v10, v10, v11
	v_cvt_pk_bf16_f32 v11, v14, v15
	v_ashrrev_i32_e32 v15, 3, v5
	ds_write_b128 v12, v[8:11] offset:18432
	v_mad_i64_i32 v[8:9], s[8:9], v15, s38, v[2:3]
	v_lshl_add_u64 v[8:9], v[8:9], 0, s[10:11]
	v_lshl_add_u64 v[8:9], v[8:9], 0, v[0:1]
	v_add_co_u32_e32 v8, vcc, s5, v8
	v_sub_u32_e32 v12, 0x7f, v15
	s_nop 0
	v_addc_co_u32_e32 v9, vcc, 0, v9, vcc
	v_cvt_f32_i32_e32 v12, v12
	v_cvt_f32_i32_e32 v13, v15
	v_mul_f32_e32 v12, v7, v12
	v_exp_f32_e32 v12, v12
	v_mul_f32_e32 v13, v6, v13
	v_exp_f32_e32 v14, v13
	s_waitcnt vmcnt(2)
	v_lshlrev_b32_e32 v16, 16, v136
	v_and_b32_e32 v17, 0xffff0000, v136
	v_pk_mul_f32 v[18:19], v[12:13], v[16:17] op_sel_hi:[0,1]
	v_cvt_pk_bf16_f32 v8, v18, v19
	v_lshlrev_b32_e32 v18, 16, v137
	v_and_b32_e32 v19, 0xffff0000, v137
	v_pk_mul_f32 v[20:21], v[12:13], v[18:19] op_sel_hi:[0,1]
	v_cvt_pk_bf16_f32 v9, v20, v21
	v_lshlrev_b32_e32 v20, 16, v138
	v_and_b32_e32 v21, 0xffff0000, v138
	v_pk_mul_f32 v[22:23], v[12:13], v[20:21] op_sel_hi:[0,1]
	v_cvt_pk_bf16_f32 v10, v22, v23
	v_lshlrev_b32_e32 v22, 16, v139
	v_and_b32_e32 v23, 0xffff0000, v139
	v_pk_mul_f32 v[12:13], v[12:13], v[22:23] op_sel_hi:[0,1]
	v_cvt_pk_bf16_f32 v11, v12, v13
	v_mad_u64_u32 v[12:13], s[8:9], v15, s30, v[0:1]
	ds_write_b128 v12, v[8:11]
	v_pk_mul_f32 v[8:9], v[14:15], v[16:17] op_sel_hi:[0,1]
	v_pk_mul_f32 v[10:11], v[14:15], v[18:19] op_sel_hi:[0,1]
	v_cvt_pk_bf16_f32 v8, v8, v9
	v_cvt_pk_bf16_f32 v9, v10, v11
	v_pk_mul_f32 v[10:11], v[14:15], v[20:21] op_sel_hi:[0,1]
	v_pk_mul_f32 v[14:15], v[14:15], v[22:23] op_sel_hi:[0,1]
	v_cvt_pk_bf16_f32 v10, v10, v11
	v_cvt_pk_bf16_f32 v11, v14, v15
	ds_write_b128 v12, v[8:11] offset:18432
	v_add_u32_e32 v8, 0x200, v51
	v_ashrrev_i32_e32 v9, 3, v8
	v_mad_i64_i32 v[10:11], s[8:9], v9, s38, v[2:3]
	v_lshl_add_u64 v[10:11], v[10:11], 0, s[10:11]
	v_lshl_add_u64 v[10:11], v[10:11], 0, v[0:1]
	v_add_co_u32_e32 v10, vcc, s5, v10
	v_sub_u32_e32 v14, 0x7f, v9
	s_nop 0
	v_addc_co_u32_e32 v11, vcc, 0, v11, vcc
	v_cvt_f32_i32_e32 v14, v14
	v_cvt_f32_i32_e32 v15, v9
	v_mul_f32_e32 v14, v7, v14
	v_exp_f32_e32 v14, v14
	v_mul_f32_e32 v15, v6, v15
	v_exp_f32_e32 v16, v15
	s_waitcnt vmcnt(1)
	v_lshlrev_b32_e32 v18, 16, v140
	v_and_b32_e32 v19, 0xffff0000, v140
	v_pk_mul_f32 v[20:21], v[14:15], v[18:19] op_sel_hi:[0,1]
	v_cvt_pk_bf16_f32 v10, v20, v21
	v_lshlrev_b32_e32 v20, 16, v141
	v_and_b32_e32 v21, 0xffff0000, v141
	v_pk_mul_f32 v[22:23], v[14:15], v[20:21] op_sel_hi:[0,1]
	v_cvt_pk_bf16_f32 v11, v22, v23
	v_lshlrev_b32_e32 v22, 16, v142
	v_and_b32_e32 v23, 0xffff0000, v142
	v_pk_mul_f32 v[24:25], v[14:15], v[22:23] op_sel_hi:[0,1]
	v_cvt_pk_bf16_f32 v12, v24, v25
	v_lshlrev_b32_e32 v24, 16, v143
	v_and_b32_e32 v25, 0xffff0000, v143
	v_pk_mul_f32 v[14:15], v[14:15], v[24:25] op_sel_hi:[0,1]
	v_cvt_pk_bf16_f32 v13, v14, v15
	v_mad_u64_u32 v[14:15], s[8:9], v9, s30, v[0:1]
	ds_write_b128 v14, v[10:13]
	v_pk_mul_f32 v[10:11], v[16:17], v[18:19] op_sel_hi:[0,1]
	v_pk_mul_f32 v[12:13], v[16:17], v[20:21] op_sel_hi:[0,1]
	v_cvt_pk_bf16_f32 v10, v10, v11
	v_cvt_pk_bf16_f32 v11, v12, v13
	v_pk_mul_f32 v[12:13], v[16:17], v[22:23] op_sel_hi:[0,1]
	v_pk_mul_f32 v[16:17], v[16:17], v[24:25] op_sel_hi:[0,1]
	v_add_u32_e32 v24, 0x300, v51
	v_cvt_pk_bf16_f32 v12, v12, v13
	v_cvt_pk_bf16_f32 v13, v16, v17
	v_ashrrev_i32_e32 v9, 3, v24
	ds_write_b128 v14, v[10:13] offset:18432
	v_mad_i64_i32 v[10:11], s[8:9], v9, s38, v[2:3]
	v_lshl_add_u64 v[10:11], v[10:11], 0, s[10:11]
	v_lshl_add_u64 v[10:11], v[10:11], 0, v[0:1]
	v_add_co_u32_e32 v10, vcc, s5, v10
	v_sub_u32_e32 v14, 0x7f, v9
	s_nop 0
	v_addc_co_u32_e32 v11, vcc, 0, v11, vcc
	v_cvt_f32_i32_e32 v14, v14
	s_mul_i32 s10, s29, 0xc0
	v_mul_f32_e32 v7, v7, v14
	v_exp_f32_e32 v14, v7
	v_cvt_f32_i32_e32 v7, v9
	v_mul_f32_e32 v6, v6, v7
	v_exp_f32_e32 v6, v6
	s_waitcnt vmcnt(0)
	v_lshlrev_b32_e32 v16, 16, v144
	v_and_b32_e32 v17, 0xffff0000, v144
	v_pk_mul_f32 v[18:19], v[14:15], v[16:17] op_sel_hi:[0,1]
	v_cvt_pk_bf16_f32 v10, v18, v19
	v_lshlrev_b32_e32 v18, 16, v145
	v_and_b32_e32 v19, 0xffff0000, v145
	v_pk_mul_f32 v[20:21], v[14:15], v[18:19] op_sel_hi:[0,1]
	v_cvt_pk_bf16_f32 v11, v20, v21
	v_lshlrev_b32_e32 v20, 16, v146
	v_and_b32_e32 v21, 0xffff0000, v146
	v_pk_mul_f32 v[22:23], v[14:15], v[20:21] op_sel_hi:[0,1]
	v_cvt_pk_bf16_f32 v12, v22, v23
	v_lshlrev_b32_e32 v22, 16, v147
	v_and_b32_e32 v23, 0xffff0000, v147
	v_pk_mul_f32 v[14:15], v[14:15], v[22:23] op_sel_hi:[0,1]
	v_cvt_pk_bf16_f32 v13, v14, v15
	v_mad_u64_u32 v[14:15], s[8:9], v9, s30, v[0:1]
	ds_write_b128 v14, v[10:13]
	v_pk_mul_f32 v[10:11], v[6:7], v[16:17] op_sel_hi:[0,1]
	v_pk_mul_f32 v[12:13], v[6:7], v[18:19] op_sel_hi:[0,1]
	v_cvt_pk_bf16_f32 v10, v10, v11
	v_cvt_pk_bf16_f32 v11, v12, v13
	v_pk_mul_f32 v[12:13], v[6:7], v[20:21] op_sel_hi:[0,1]
	v_pk_mul_f32 v[6:7], v[6:7], v[22:23] op_sel_hi:[0,1]
	v_mul_hi_i32 v0, v51, s31
	v_cvt_pk_bf16_f32 v12, v12, v13
	v_cvt_pk_bf16_f32 v13, v6, v7
	v_lshrrev_b32_e32 v6, 31, v0
	v_ashrrev_i32_e32 v0, 1, v0
	v_add_u32_e32 v0, v0, v6
	v_mul_lo_u32 v6, v0, 12
	v_sub_u32_e32 v9, v51, v6
	ds_write_b128 v14, v[10:13] offset:18432
	v_mad_i64_i32 v[6:7], s[8:9], v0, s38, v[2:3]
	v_lshlrev_b32_e32 v10, 3, v9
	v_lshl_add_u64 v[6:7], v[6:7], 0, s[10:11]
	v_ashrrev_i32_e32 v11, 31, v10
	v_lshl_add_u64 v[6:7], v[10:11], 1, v[6:7]
	v_add_co_u32_e32 v6, vcc, s5, v6
	v_mul_lo_u32 v0, v0, s36
	s_nop 0
	v_addc_co_u32_e32 v7, vcc, 0, v7, vcc
	global_load_dwordx4 v[148:151], v[6:7], off offset:2048
	v_lshl_add_u32 v172, v9, 4, v0
	v_mul_hi_i32 v0, v5, s31
	v_lshrrev_b32_e32 v6, 31, v0
	v_ashrrev_i32_e32 v0, 1, v0
	v_add_u32_e32 v0, v0, v6
	v_mul_lo_u32 v6, v0, 12
	v_sub_u32_e32 v5, v5, v6
	v_mad_i64_i32 v[6:7], s[8:9], v0, s38, v[2:3]
	v_lshlrev_b32_e32 v10, 3, v5
	v_lshl_add_u64 v[6:7], v[6:7], 0, s[10:11]
	v_ashrrev_i32_e32 v11, 31, v10
	v_lshl_add_u64 v[6:7], v[10:11], 1, v[6:7]
	v_add_co_u32_e32 v6, vcc, s5, v6
	v_mul_lo_u32 v0, v0, s36
	s_nop 0
	v_addc_co_u32_e32 v7, vcc, 0, v7, vcc
	global_load_dwordx4 v[152:155], v[6:7], off offset:2048
	v_lshl_add_u32 v173, v5, 4, v0
	v_mul_hi_i32 v0, v8, s31
	v_lshrrev_b32_e32 v5, 31, v0
	v_ashrrev_i32_e32 v0, 1, v0
	v_add_u32_e32 v0, v0, v5
	v_mul_lo_u32 v5, v0, 12
	v_sub_u32_e32 v5, v8, v5
	v_mad_i64_i32 v[6:7], s[8:9], v0, s38, v[2:3]
	v_lshlrev_b32_e32 v8, 3, v5
	v_lshl_add_u64 v[6:7], v[6:7], 0, s[10:11]
	v_ashrrev_i32_e32 v9, 31, v8
	v_lshl_add_u64 v[6:7], v[8:9], 1, v[6:7]
	v_add_co_u32_e32 v6, vcc, s5, v6
	v_mul_lo_u32 v0, v0, s36
	s_nop 0
	v_addc_co_u32_e32 v7, vcc, 0, v7, vcc
	global_load_dwordx4 v[156:159], v[6:7], off offset:2048
	v_lshl_add_u32 v174, v5, 4, v0
	v_mul_hi_i32 v0, v24, s31
	v_lshrrev_b32_e32 v5, 31, v0
	v_ashrrev_i32_e32 v0, 1, v0
	v_add_u32_e32 v0, v0, v5
	v_mul_lo_u32 v5, v0, 12
	v_sub_u32_e32 v5, v24, v5
	v_mad_i64_i32 v[6:7], s[8:9], v0, s38, v[2:3]
	v_lshlrev_b32_e32 v8, 3, v5
	v_lshl_add_u64 v[6:7], v[6:7], 0, s[10:11]
	v_ashrrev_i32_e32 v9, 31, v8
	v_lshl_add_u64 v[6:7], v[8:9], 1, v[6:7]
	v_add_co_u32_e32 v6, vcc, s5, v6
	v_mul_lo_u32 v0, v0, s36
	s_nop 0
	v_addc_co_u32_e32 v7, vcc, 0, v7, vcc
	global_load_dwordx4 v[160:163], v[6:7], off offset:2048
	v_lshl_add_u32 v175, v5, 4, v0
	v_add_u32_e32 v0, 0x400, v51
	v_mul_hi_i32 v5, v0, s31
	v_lshrrev_b32_e32 v6, 31, v5
	v_ashrrev_i32_e32 v5, 1, v5
	v_add_u32_e32 v5, v5, v6
	v_mul_lo_u32 v6, v5, 12
	v_sub_u32_e32 v0, v0, v6
	v_mad_i64_i32 v[6:7], s[8:9], v5, s38, v[2:3]
	v_lshlrev_b32_e32 v8, 3, v0
	v_lshl_add_u64 v[6:7], v[6:7], 0, s[10:11]
	v_ashrrev_i32_e32 v9, 31, v8
	v_lshl_add_u64 v[6:7], v[8:9], 1, v[6:7]
	v_add_co_u32_e32 v6, vcc, s5, v6
	v_mul_lo_u32 v5, v5, s36
	s_nop 0
	v_addc_co_u32_e32 v7, vcc, 0, v7, vcc
	global_load_dwordx4 v[164:167], v[6:7], off offset:2048
	v_lshl_add_u32 v176, v0, 4, v5
	v_add_u32_e32 v0, 0x500, v51
	v_mul_hi_i32 v5, v0, s31
	v_lshrrev_b32_e32 v6, 31, v5
	v_ashrrev_i32_e32 v5, 1, v5
	v_add_u32_e32 v5, v5, v6
	v_mul_lo_u32 v6, v5, 12
	v_sub_u32_e32 v0, v0, v6
	v_mad_i64_i32 v[2:3], s[8:9], v5, s38, v[2:3]
	v_lshlrev_b32_e32 v6, 3, v0
	v_lshl_add_u64 v[2:3], v[2:3], 0, s[10:11]
	v_ashrrev_i32_e32 v7, 31, v6
	v_lshl_add_u64 v[2:3], v[6:7], 1, v[2:3]
	v_add_co_u32_e32 v2, vcc, s5, v2
	s_movk_i32 s5, 0x80
	s_nop 0
	v_addc_co_u32_e32 v3, vcc, 0, v3, vcc
	global_load_dwordx4 v[168:171], v[2:3], off offset:2048
	v_mul_lo_u32 v2, v5, s36
	v_lshrrev_b32_e32 v3, 3, v51
	v_lshl_add_u32 v177, v0, 4, v2
	v_and_b32_e32 v52, 4, v3
	v_lshrrev_b32_e32 v3, 2, v51
	v_cmp_gt_u32_e32 vcc, s5, v51
	v_and_or_b32 v6, v3, 3, v52
	v_lshlrev_b32_e32 v3, 1, v51
	v_bfe_u32 v0, v51, 6, 1
	v_cndmask_b32_e64 v2, v210, 0, vcc
	v_and_b32_e32 v3, 32, v3
	v_or_b32_e32 v2, v2, v3
	v_lshlrev_b32_e32 v5, 6, v0
	v_or3_b32 v2, v2, v5, v4
	v_or_b32_e32 v7, v3, v4
	v_mad_u32_u24 v53, v6, s30, v2
	v_mad_u32_u24 v62, v6, s36, v7
	s_waitcnt vmcnt(5)
	ds_write_b128 v172, v[148:151] offset:36864
	s_waitcnt vmcnt(4)
	ds_write_b128 v173, v[152:155] offset:36864
	s_waitcnt vmcnt(3)
	ds_write_b128 v174, v[156:159] offset:36864
	s_waitcnt vmcnt(2)
	ds_write_b128 v175, v[160:163] offset:36864
	s_waitcnt vmcnt(1)
	ds_write_b128 v176, v[164:167] offset:36864
	s_waitcnt vmcnt(0)
	ds_write_b128 v177, v[168:171] offset:36864
	s_waitcnt lgkmcnt(0)
	s_barrier
	ds_read_b64_tr_b16 v[130:131], v53
	ds_read_b64_tr_b16 v[132:133], v53 offset:1152
	ds_read_b64_tr_b16 v[138:139], v62 offset:36864
	ds_read_b64_tr_b16 v[140:141], v62 offset:38528
	ds_read_b64_tr_b16 v[142:143], v62 offset:36928
	ds_read_b64_tr_b16 v[144:145], v62 offset:38592
	ds_read_b64_tr_b16 v[146:147], v62 offset:36992
	ds_read_b64_tr_b16 v[148:149], v62 offset:38656
	ds_read_b64_tr_b16 v[134:135], v53 offset:2304
	ds_read_b64_tr_b16 v[136:137], v53 offset:3456
	ds_read_b64_tr_b16 v[150:151], v62 offset:40192
	ds_read_b64_tr_b16 v[152:153], v62 offset:41856
	ds_read_b64_tr_b16 v[154:155], v62 offset:40256
	ds_read_b64_tr_b16 v[156:157], v62 offset:41920
	s_waitcnt lgkmcnt(12)
	s_waitcnt lgkmcnt(10)
	v_mfma_f32_32x32x16_bf16 v[34:49], v[138:141], v[130:133], 0
	ds_read_b64_tr_b16 v[158:159], v62 offset:40320
	ds_read_b64_tr_b16 v[160:161], v62 offset:41984
	s_waitcnt lgkmcnt(10)
	v_mfma_f32_32x32x16_bf16 v[18:33], v[142:145], v[130:133], 0
	s_waitcnt lgkmcnt(8)
	v_mfma_f32_32x32x16_bf16 v[2:17], v[146:149], v[130:133], 0
	ds_read_b64_tr_b16 v[130:131], v53 offset:4608
	ds_read_b64_tr_b16 v[132:133], v53 offset:5760
	ds_read_b64_tr_b16 v[138:139], v62 offset:43520
	ds_read_b64_tr_b16 v[140:141], v62 offset:45184
	ds_read_b64_tr_b16 v[142:143], v62 offset:43584
	ds_read_b64_tr_b16 v[144:145], v62 offset:45248
	s_waitcnt lgkmcnt(12)
	s_waitcnt lgkmcnt(10)
	v_mfma_f32_32x32x16_bf16 v[34:49], v[150:153], v[134:137], v[34:49]
	ds_read_b64_tr_b16 v[146:147], v62 offset:43648
	ds_read_b64_tr_b16 v[148:149], v62 offset:45312
	s_waitcnt lgkmcnt(10)
	v_mfma_f32_32x32x16_bf16 v[18:33], v[154:157], v[134:137], v[18:33]
	s_waitcnt lgkmcnt(8)
	v_mfma_f32_32x32x16_bf16 v[2:17], v[158:161], v[134:137], v[2:17]
	ds_read_b64_tr_b16 v[134:135], v53 offset:6912
	ds_read_b64_tr_b16 v[136:137], v53 offset:8064
	ds_read_b64_tr_b16 v[150:151], v62 offset:46848
	ds_read_b64_tr_b16 v[152:153], v62 offset:48512
	ds_read_b64_tr_b16 v[154:155], v62 offset:46912
	ds_read_b64_tr_b16 v[156:157], v62 offset:48576
	s_waitcnt lgkmcnt(12)
	s_waitcnt lgkmcnt(10)
	v_mfma_f32_32x32x16_bf16 v[34:49], v[138:141], v[130:133], v[34:49]
	ds_read_b64_tr_b16 v[158:159], v62 offset:46976
	ds_read_b64_tr_b16 v[160:161], v62 offset:48640
	s_waitcnt lgkmcnt(10)
	v_mfma_f32_32x32x16_bf16 v[18:33], v[142:145], v[130:133], v[18:33]
	s_waitcnt lgkmcnt(8)
	v_mfma_f32_32x32x16_bf16 v[2:17], v[146:149], v[130:133], v[2:17]
	ds_read_b64_tr_b16 v[130:131], v53 offset:9216
	ds_read_b64_tr_b16 v[132:133], v53 offset:10368
	ds_read_b64_tr_b16 v[138:139], v62 offset:50176
	ds_read_b64_tr_b16 v[140:141], v62 offset:51840
	ds_read_b64_tr_b16 v[142:143], v62 offset:50240
	ds_read_b64_tr_b16 v[144:145], v62 offset:51904
	s_waitcnt lgkmcnt(12)
	s_waitcnt lgkmcnt(10)
	v_mfma_f32_32x32x16_bf16 v[34:49], v[150:153], v[134:137], v[34:49]
	ds_read_b64_tr_b16 v[146:147], v62 offset:50304
	ds_read_b64_tr_b16 v[148:149], v62 offset:51968
	s_waitcnt lgkmcnt(10)
	v_mfma_f32_32x32x16_bf16 v[18:33], v[154:157], v[134:137], v[18:33]
	s_waitcnt lgkmcnt(8)
	v_mfma_f32_32x32x16_bf16 v[2:17], v[158:161], v[134:137], v[2:17]
	ds_read_b64_tr_b16 v[134:135], v53 offset:11520
	ds_read_b64_tr_b16 v[136:137], v53 offset:12672
	ds_read_b64_tr_b16 v[150:151], v62 offset:53504
	ds_read_b64_tr_b16 v[152:153], v62 offset:55168
	ds_read_b64_tr_b16 v[154:155], v62 offset:53568
	ds_read_b64_tr_b16 v[156:157], v62 offset:55232
	s_waitcnt lgkmcnt(12)
	s_waitcnt lgkmcnt(10)
	v_mfma_f32_32x32x16_bf16 v[34:49], v[138:141], v[130:133], v[34:49]
	ds_read_b64_tr_b16 v[158:159], v62 offset:53632
	ds_read_b64_tr_b16 v[160:161], v62 offset:55296
	s_waitcnt lgkmcnt(10)
	v_mfma_f32_32x32x16_bf16 v[18:33], v[142:145], v[130:133], v[18:33]
	s_waitcnt lgkmcnt(8)
	v_mfma_f32_32x32x16_bf16 v[2:17], v[146:149], v[130:133], v[2:17]
	ds_read_b64_tr_b16 v[130:131], v53 offset:13824
	ds_read_b64_tr_b16 v[132:133], v53 offset:14976
	ds_read_b64_tr_b16 v[138:139], v62 offset:56832
	ds_read_b64_tr_b16 v[140:141], v62 offset:58496
	ds_read_b64_tr_b16 v[142:143], v62 offset:56896
	ds_read_b64_tr_b16 v[144:145], v62 offset:58560
	s_waitcnt lgkmcnt(12)
	s_waitcnt lgkmcnt(10)
	v_mfma_f32_32x32x16_bf16 v[34:49], v[150:153], v[134:137], v[34:49]
	ds_read_b64_tr_b16 v[146:147], v62 offset:56960
	ds_read_b64_tr_b16 v[148:149], v62 offset:58624
	s_waitcnt lgkmcnt(10)
	v_mfma_f32_32x32x16_bf16 v[18:33], v[154:157], v[134:137], v[18:33]
	s_waitcnt lgkmcnt(8)
	v_mfma_f32_32x32x16_bf16 v[2:17], v[158:161], v[134:137], v[2:17]
	ds_read_b64_tr_b16 v[134:135], v53 offset:16128
	ds_read_b64_tr_b16 v[136:137], v53 offset:17280
	ds_read_b64_tr_b16 v[150:151], v62 offset:60160
	ds_read_b64_tr_b16 v[152:153], v62 offset:61824
	ds_read_b64_tr_b16 v[154:155], v62 offset:60224
	ds_read_b64_tr_b16 v[156:157], v62 offset:61888
	s_waitcnt lgkmcnt(12)
	s_waitcnt lgkmcnt(10)
	v_mfma_f32_32x32x16_bf16 v[34:49], v[138:141], v[130:133], v[34:49]
	ds_read_b64_tr_b16 v[158:159], v62 offset:60288
	ds_read_b64_tr_b16 v[160:161], v62 offset:61952
	v_and_b32_e32 v53, 31, v51
	v_lshl_or_b32 v0, v0, 5, v53
	v_cmp_gt_u32_e32 vcc, 48, v0
	s_waitcnt lgkmcnt(10)
	v_mfma_f32_32x32x16_bf16 v[18:33], v[142:145], v[130:133], v[18:33]
	s_waitcnt lgkmcnt(8)
	v_mfma_f32_32x32x16_bf16 v[2:17], v[146:149], v[130:133], v[2:17]
	s_waitcnt lgkmcnt(6)
	s_waitcnt lgkmcnt(4)
	v_mfma_f32_32x32x16_bf16 v[34:49], v[150:153], v[134:137], v[34:49]
	s_waitcnt lgkmcnt(2)
	v_mfma_f32_32x32x16_bf16 v[18:33], v[154:157], v[134:137], v[18:33]
	s_waitcnt lgkmcnt(0)
	v_mfma_f32_32x32x16_bf16 v[2:17], v[158:161], v[134:137], v[2:17]
	s_and_saveexec_b64 s[8:9], vcc
	s_cbranch_execz .LBB0_66
	s_lshl_b32 s4, s4, 2
	s_or_b32 s4, s4, s29
	s_ashr_i32 s5, s4, 31
	v_ashrrev_i32_e32 v54, 7, v51
	s_lshl_b64 s[4:5], s[4:5], 6
	s_lshl_b32 s10, s28, 1
	s_or_b32 s4, s4, s10
	v_ashrrev_i32_e32 v55, 31, v54
	v_lshl_add_u64 v[54:55], s[4:5], 0, v[54:55]
	v_mov_b64_e32 v[56:57], s[0:1]
	s_movk_i32 s4, 0x4800
	v_mad_u64_u32 v[56:57], s[0:1], v54, s4, v[56:57]
	v_mad_i32_i24 v57, v55, s4, v57
	v_lshlrev_b32_e32 v0, 2, v0
	v_lshl_add_u64 v[54:55], v[56:57], 0, v[0:1]
	v_mul_u32_u24_e32 v0, 48, v52
	v_lshlrev_b32_e32 v0, 2, v0
	v_lshl_add_u64 v[52:53], v[54:55], 0, v[0:1]
	s_movk_i32 s0, 0x1000
	global_store_dword v[52:53], v34, off sc1
	global_store_dword v[52:53], v35, off offset:192 sc1
	global_store_dword v[52:53], v36, off offset:384 sc1
	global_store_dword v[52:53], v37, off offset:576 sc1
	global_store_dword v[52:53], v38, off offset:1536 sc1
	global_store_dword v[52:53], v39, off offset:1728 sc1
	global_store_dword v[52:53], v40, off offset:1920 sc1
	global_store_dword v[52:53], v41, off offset:2112 sc1
	global_store_dword v[52:53], v42, off offset:3072 sc1
	global_store_dword v[52:53], v43, off offset:3264 sc1
	global_store_dword v[52:53], v44, off offset:3456 sc1
	global_store_dword v[52:53], v45, off offset:3648 sc1
	v_add_co_u32_e32 v34, vcc, s0, v52
	s_movk_i32 s0, 0x2000
	s_nop 0
	v_addc_co_u32_e32 v35, vcc, 0, v53, vcc
	global_store_dword v[34:35], v46, off offset:512 sc1
	global_store_dword v[34:35], v47, off offset:704 sc1
	global_store_dword v[34:35], v48, off offset:896 sc1
	global_store_dword v[34:35], v49, off offset:1088 sc1
	global_store_dword v[34:35], v18, off offset:2048 sc1
	global_store_dword v[34:35], v19, off offset:2240 sc1
	global_store_dword v[34:35], v20, off offset:2432 sc1
	global_store_dword v[34:35], v21, off offset:2624 sc1
	global_store_dword v[34:35], v22, off offset:3584 sc1
	global_store_dword v[34:35], v23, off offset:3776 sc1
	global_store_dword v[34:35], v24, off offset:3968 sc1
	v_add_co_u32_e32 v18, vcc, s0, v52
	s_nop 1
	v_addc_co_u32_e32 v19, vcc, 0, v53, vcc
	global_store_dword v[18:19], v25, off offset:64 sc1
	global_store_dword v[18:19], v26, off offset:1024 sc1
	global_store_dword v[18:19], v27, off offset:1216 sc1
	global_store_dword v[18:19], v28, off offset:1408 sc1
	global_store_dword v[18:19], v29, off offset:1600 sc1
	global_store_dword v[18:19], v30, off offset:2560 sc1
	global_store_dword v[18:19], v31, off offset:2752 sc1
	global_store_dword v[18:19], v32, off offset:2944 sc1
	global_store_dword v[18:19], v33, off offset:3136 sc1
	v_add_co_u32_e32 v18, vcc, s73, v52
	s_nop 1
	v_addc_co_u32_e32 v19, vcc, 0, v53, vcc
	global_store_dword v[18:19], v2, off sc1
	global_store_dword v[18:19], v3, off offset:192 sc1
	global_store_dword v[18:19], v4, off offset:384 sc1
	global_store_dword v[18:19], v5, off offset:576 sc1
	global_store_dword v[18:19], v6, off offset:1536 sc1
	global_store_dword v[18:19], v7, off offset:1728 sc1
	global_store_dword v[18:19], v8, off offset:1920 sc1
	global_store_dword v[18:19], v9, off offset:2112 sc1
	global_store_dword v[18:19], v10, off offset:3072 sc1
	global_store_dword v[18:19], v11, off offset:3264 sc1
	global_store_dword v[18:19], v12, off offset:3456 sc1
	global_store_dword v[18:19], v13, off offset:3648 sc1
	v_add_co_u32_e32 v2, vcc, 0x4000, v52
	s_nop 1
	v_addc_co_u32_e32 v3, vcc, 0, v53, vcc
	global_store_dword v[2:3], v14, off offset:512 sc1
	global_store_dword v[2:3], v15, off offset:704 sc1
	global_store_dword v[2:3], v16, off offset:896 sc1
	global_store_dword v[2:3], v17, off offset:1088 sc1
